# as the previous version plus the FFT spectrum-multiply loop's two 16-byte loads fetched one iteration ahead (landing v236..v243)
# baseline (speedup 1.0000x reference)
.LBB0_680:
	s_or_b64 exec, exec, s[12:13]
	v_readlane_b32 s12, v254, 20
	v_readlane_b32 s13, v254, 21
	s_and_b64 exec, exec, s[12:13]
	s_cbranch_execz .LBB0_691
	v_readlane_b32 s12, v253, 59
	v_ashrrev_i32_e32 v3, 31, v2
	v_readlane_b32 s13, v253, 60
	v_add_u32_e32 v31, 0xfffffc00, v2
	v_lshl_add_u32 v0, v2, 4, 0
	v_lshlrev_b32_e32 v25, 1, v2
	v_lshl_add_u64 v[2:3], v[2:3], 4, s[12:13]
	v_add_co_u32_e32 v244, vcc, 0xffffe000, v2
	s_nop 1
	v_addc_co_u32_e32 v245, vcc, -1, v3, vcc
	global_load_dwordx4 v[236:239], v[244:245], off
	global_load_dwordx4 v[240:243], v[2:3], off
	s_mov_b64 s[12:13], 0
	s_branch .LBB0_683

.LBB0_683:
	v_add_co_u32_e32 v20, vcc, 0xffffe000, v2
	v_bfrev_b32_e32 v32, v25
	s_nop 0
	v_addc_co_u32_e32 v21, vcc, -1, v3, vcc
	s_waitcnt vmcnt(1)
	v_lshl_add_u64 v[244:245], v[20:21], 0, s[92:93]
	v_mov_b32_e32 v20, v236
	v_mov_b32_e32 v21, v237
	v_mov_b32_e32 v22, v238
	v_mov_b32_e32 v23, v239
	global_load_dwordx4 v[236:239], v[244:245], off
	v_add_u32_e32 v30, 0x400, v31
	v_cmp_lt_u32_e32 vcc, s36, v32
	s_and_saveexec_b64 s[20:21], vcc
	s_xor_b64 s[82:83], exec, s[20:21]
	s_cbranch_execz .LBB0_685
	v_lshrrev_b32_e32 v32, 18, v32
	v_sub_u32_e32 v32, 0x4000, v32
	v_bfrev_b32_e32 v34, v32
	v_lshrrev_b32_e32 v35, 15, v34
	v_lshrrev_b32_e32 v34, 20, v34
	v_ashrrev_i32_e32 v32, 4, v30
	v_and_b32_e32 v35, 0x1fff8, v35
	v_and_b32_e32 v34, 0xff8, v34
	v_lshl_add_u32 v44, v32, 3, v0
	v_add3_u32 v45, 0, v35, v34
	ds_read_b64 v[32:33], v44
	ds_read_b64 v[34:35], v45
	s_mov_b32 s20, s49
	s_mov_b32 s21, s48
	v_mov_b32_e32 v42, v21
	v_mov_b32_e32 v43, v23
	s_waitcnt lgkmcnt(0)
	v_pk_add_f32 v[36:37], v[32:33], v[34:35]
	v_pk_add_f32 v[32:33], v[32:33], v[34:35] neg_lo:[0,1] neg_hi:[0,1]
	v_pk_mul_f32 v[34:35], v[36:37], 0.5 op_sel_hi:[1,0]
	v_pk_mul_f32 v[40:41], v[32:33], s[20:21]
	v_mov_b32_e32 v38, v37
	v_mov_b32_e32 v39, v33
	v_mov_b32_e32 v33, v36
	v_mov_b32_e32 v36, v20
	v_mov_b32_e32 v37, v22
	v_pk_mul_f32 v[40:41], v[42:43], v[40:41] op_sel:[0,1] op_sel_hi:[1,0]
	v_pk_mul_f32 v[38:39], v[38:39], 0.5 op_sel_hi:[1,0]
	v_pk_fma_f32 v[34:35], v[36:37], v[34:35], v[40:41] neg_lo:[0,0,1] neg_hi:[0,0,1]
	v_mov_b32_e32 v36, v23
	v_mov_b32_e32 v37, v20
	v_pk_mul_f32 v[32:33], v[32:33], s[20:21]
	v_pk_mul_f32 v[36:37], v[36:37], v[38:39]
	v_mov_b32_e32 v23, v21
	v_pk_fma_f32 v[20:21], v[22:23], v[32:33], v[36:37]
	s_nop 0
	v_pk_add_f32 v[22:23], v[34:35], v[20:21] neg_lo:[0,1] neg_hi:[0,1]
	v_pk_add_f32 v[20:21], v[34:35], v[20:21]
	v_mov_b32_e32 v32, v22
	v_mov_b32_e32 v33, v21
	v_mov_b32_e32 v21, v23
	ds_write_b64 v44, v[32:33]
	ds_write_b64 v45, v[20:21]

.LBB0_687:
	s_or_b64 exec, exec, s[82:83]
	v_add_u32_e32 v20, 0x400, v25
	v_bfrev_b32_e32 v32, v20
	s_waitcnt vmcnt(1)
	v_lshl_add_u64 v[244:245], v[2:3], 0, s[92:93]
	v_mov_b32_e32 v20, v240
	v_mov_b32_e32 v21, v241
	v_mov_b32_e32 v22, v242
	v_mov_b32_e32 v23, v243
	global_load_dwordx4 v[240:243], v[244:245], off
	v_cmp_lt_u32_e32 vcc, s36, v32
	s_and_saveexec_b64 s[20:21], vcc
	s_xor_b64 s[82:83], exec, s[20:21]
	s_cbranch_execz .LBB0_689
	v_lshrrev_b32_e32 v32, 18, v32
	v_sub_u32_e32 v32, 0x4000, v32
	v_bfrev_b32_e32 v34, v32
	v_add_u32_e32 v31, 0x600, v31
	v_lshrrev_b32_e32 v35, 15, v34
	v_lshrrev_b32_e32 v34, 20, v34
	v_ashrrev_i32_e32 v31, 4, v31
	v_and_b32_e32 v35, 0x1fff8, v35
	v_and_b32_e32 v34, 0xff8, v34
	v_lshl_add_u32 v31, v31, 3, v0
	v_add3_u32 v44, 0, v35, v34
	ds_read_b64 v[32:33], v31 offset:8192
	ds_read_b64 v[34:35], v44
	s_mov_b32 s20, s49
	s_mov_b32 s21, s48
	v_mov_b32_e32 v42, v21
	v_mov_b32_e32 v43, v23
	s_waitcnt lgkmcnt(0)
	v_pk_add_f32 v[36:37], v[32:33], v[34:35]
	v_pk_add_f32 v[32:33], v[32:33], v[34:35] neg_lo:[0,1] neg_hi:[0,1]
	v_pk_mul_f32 v[34:35], v[36:37], 0.5 op_sel_hi:[1,0]
	v_pk_mul_f32 v[40:41], v[32:33], s[20:21]
	v_mov_b32_e32 v38, v37
	v_mov_b32_e32 v39, v33
	v_mov_b32_e32 v33, v36
	v_mov_b32_e32 v36, v20
	v_mov_b32_e32 v37, v22
	v_pk_mul_f32 v[40:41], v[42:43], v[40:41] op_sel:[0,1] op_sel_hi:[1,0]
	v_pk_mul_f32 v[38:39], v[38:39], 0.5 op_sel_hi:[1,0]
	v_pk_fma_f32 v[34:35], v[36:37], v[34:35], v[40:41] neg_lo:[0,0,1] neg_hi:[0,0,1]
	v_mov_b32_e32 v36, v23
	v_mov_b32_e32 v37, v20
	v_pk_mul_f32 v[32:33], v[32:33], s[20:21]
	v_pk_mul_f32 v[36:37], v[36:37], v[38:39]
	v_mov_b32_e32 v23, v21
	v_pk_fma_f32 v[20:21], v[22:23], v[32:33], v[36:37]
	s_nop 0
	v_pk_add_f32 v[22:23], v[34:35], v[20:21] neg_lo:[0,1] neg_hi:[0,1]
	v_pk_add_f32 v[20:21], v[34:35], v[20:21]
	v_mov_b32_e32 v32, v22
	v_mov_b32_e32 v33, v21
	v_mov_b32_e32 v21, v23
	ds_write_b64 v31, v[32:33] offset:8192
	ds_write_b64 v44, v[20:21]

.LBB0_691:
	s_or_b64 exec, exec, s[2:3]
	s_waitcnt vmcnt(0)
	v_mov_b32_e32 v3, v24
	s_waitcnt lgkmcnt(0)
	s_barrier
	s_nop 0
	v_cmp_gt_i32_e32 vcc, s47, v3
	s_and_saveexec_b64 s[2:3], vcc
	s_cbranch_execz .LBB0_694
	v_add_u32_e32 v0, 0xfffffe00, v3
	v_lshl_add_u32 v2, v3, 5, 0
	v_lshlrev_b32_e32 v3, 2, v3
	s_mov_b64 s[12:13], 0
